# P3: batch the 8 serialized ratio-hook and 8 SR-epilogue load rounds (12 loads up front, counted vmcnt)
# speedup vs baseline: 1.0066x; 1.0066x over previous
.LBB0_780:
	s_cmpk_lg_i32 s64, 0x400
	s_cbranch_scc1 .LBB0_779
	v_mov_b32_e32 v4, v178
	v_mov_b32_e32 v184, v5
	v_lshl_add_u64 v[6:7], v[4:5], 1, s[44:45]
	v_lshl_add_u64 v[196:197], v[6:7], 0, v[148:149]
	global_load_dwordx4 v[196:199], v[196:197], off
	v_lshl_add_u64 v[200:201], v[6:7], 0, v[150:151]
	global_load_dwordx4 v[200:203], v[200:201], off
	s_mov_b64 s[26:27], 0x8000
	v_lshl_add_u64 v[204:205], v[6:7], 0, s[26:27]
	v_lshl_add_u64 v[206:207], v[204:205], 0, v[150:151]
	global_load_dwordx4 v[204:207], v[206:207], off
	s_mov_b64 s[26:27], 0x8000
	v_lshl_add_u64 v[208:209], v[6:7], 0, s[26:27]
	v_lshl_add_u64 v[208:209], v[208:209], 0, v[148:149]
	global_load_dwordx4 v[208:211], v[208:209], off
	s_mov_b64 s[26:27], 0x10000
	v_lshl_add_u64 v[212:213], v[6:7], 0, s[26:27]
	v_lshl_add_u64 v[214:215], v[212:213], 0, v[148:149]
	global_load_dwordx4 v[212:215], v[214:215], off
	s_mov_b64 s[26:27], 0x10000
	v_lshl_add_u64 v[216:217], v[6:7], 0, s[26:27]
	v_lshl_add_u64 v[218:219], v[216:217], 0, v[150:151]
	global_load_dwordx4 v[216:219], v[218:219], off
	v_lshl_add_u64 v[220:221], v[6:7], 0, s[14:15]
	v_lshl_add_u64 v[222:223], v[220:221], 0, v[150:151]
	global_load_dwordx4 v[220:223], v[222:223], off
	v_lshl_add_u64 v[224:225], v[6:7], 0, s[14:15]
	v_lshl_add_u64 v[224:225], v[224:225], 0, v[148:149]
	global_load_dwordx4 v[224:227], v[224:225], off
	s_mov_b64 s[26:27], 0x40000
	v_lshl_add_u64 v[228:229], v[6:7], 0, s[26:27]
	v_lshl_add_u64 v[230:231], v[228:229], 0, v[148:149]
	global_load_dwordx4 v[228:231], v[230:231], off
	s_mov_b64 s[26:27], 0x40000
	v_lshl_add_u64 v[232:233], v[6:7], 0, s[26:27]
	v_lshl_add_u64 v[234:235], v[232:233], 0, v[150:151]
	global_load_dwordx4 v[232:235], v[234:235], off
	s_mov_b64 s[26:27], 0x48000
	v_lshl_add_u64 v[236:237], v[6:7], 0, s[26:27]
	v_lshl_add_u64 v[238:239], v[236:237], 0, v[150:151]
	global_load_dwordx4 v[236:239], v[238:239], off
	s_mov_b64 s[26:27], 0x48000
	v_lshl_add_u64 v[240:241], v[6:7], 0, s[26:27]
	v_lshl_add_u64 v[240:241], v[240:241], 0, v[148:149]
	global_load_dwordx4 v[240:243], v[240:241], off
	v_lshl_add_u64 v[136:137], v[6:7], 0, v[148:149]
	v_lshl_add_u64 v[140:141], v[6:7], 0, v[150:151]
	v_mov_b32_e32 v182, v5
	v_mov_b32_e32 v183, v5
	v_mov_b32_e32 v185, v5
	s_mov_b64 s[26:27], 0x8000
	s_waitcnt vmcnt(10)
	v_cndmask_b32_e64 v180, v202, v198, s[8:9]
	v_cndmask_b32_e64 v138, v198, v202, s[8:9]
	v_cndmask_b32_e64 v4, v200, v196, s[8:9]
	v_cndmask_b32_e64 v179, v201, v197, s[8:9]
	v_cndmask_b32_e64 v136, v196, v200, s[8:9]
	v_cndmask_b32_e64 v137, v197, v201, s[8:9]
	v_mov_b32_dpp v184, v138 row_ror:8 row_mask:0xf bank_mask:0xf
	v_lshlrev_b32_e32 v140, 16, v180
	v_and_b32_e32 v141, 0xffff0000, v180
	v_cndmask_b32_e64 v181, v203, v199, s[8:9]
	v_cndmask_b32_e64 v139, v199, v203, s[8:9]
	s_mov_b64 s[26:27], 0x50000
	v_lshl_add_u64 v[196:197], v[6:7], 0, s[26:27]
	v_lshl_add_u64 v[198:199], v[196:197], 0, v[148:149]
	global_load_dwordx4 v[196:199], v[198:199], off
	s_mov_b64 s[26:27], 0x50000
	v_lshl_add_u64 v[200:201], v[6:7], 0, s[26:27]
	v_lshl_add_u64 v[202:203], v[200:201], 0, v[150:151]
	global_load_dwordx4 v[200:203], v[202:203], off
	v_mov_b32_dpp v182, v136 row_ror:8 row_mask:0xf bank_mask:0xf
	v_mov_b32_dpp v183, v137 row_ror:8 row_mask:0xf bank_mask:0xf
	v_lshlrev_b32_e32 v136, 16, v4
	v_and_b32_e32 v137, 0xffff0000, v4
	v_pk_mul_f32 v[128:129], v[128:129], v[140:141]
	v_lshlrev_b32_e32 v140, 16, v184
	v_and_b32_e32 v141, 0xffff0000, v184
	v_mov_b32_dpp v185, v139 row_ror:8 row_mask:0xf bank_mask:0xf
	v_lshlrev_b32_e32 v138, 16, v179
	v_and_b32_e32 v139, 0xffff0000, v179
	v_lshlrev_b32_e32 v142, 16, v181
	v_and_b32_e32 v143, 0xffff0000, v181
	v_pk_mul_f32 v[132:133], v[132:133], v[136:137]
	v_lshlrev_b32_e32 v136, 16, v182
	v_and_b32_e32 v137, 0xffff0000, v182
	v_pk_mul_f32 v[120:121], v[120:121], v[140:141]
	v_lshl_add_u64 v[140:141], v[6:7], 0, s[26:27]
	v_pk_mul_f32 v[134:135], v[134:135], v[138:139]
	v_pk_mul_f32 v[130:131], v[130:131], v[142:143]
	v_lshlrev_b32_e32 v138, 16, v183
	v_and_b32_e32 v139, 0xffff0000, v183
	v_lshlrev_b32_e32 v142, 16, v185
	v_and_b32_e32 v143, 0xffff0000, v185
	v_pk_mul_f32 v[124:125], v[124:125], v[136:137]
	v_lshl_add_u64 v[136:137], v[140:141], 0, v[150:151]
	v_lshl_add_u64 v[140:141], v[140:141], 0, v[148:149]
	v_pk_mul_f32 v[126:127], v[126:127], v[138:139]
	v_pk_mul_f32 v[122:123], v[122:123], v[142:143]
	v_mov_b32_e32 v182, v5
	v_mov_b32_e32 v183, v5
	v_mov_b32_e32 v184, v5
	v_mov_b32_e32 v185, v5
	s_mov_b64 s[26:27], 0x10000
	s_waitcnt vmcnt(10)
	v_cndmask_b32_e64 v4, v204, v208, s[8:9]
	v_cndmask_b32_e64 v179, v205, v209, s[8:9]
	v_cndmask_b32_e64 v136, v208, v204, s[8:9]
	v_cndmask_b32_e64 v137, v209, v205, s[8:9]
	v_cndmask_b32_e64 v180, v206, v210, s[8:9]
	v_cndmask_b32_e64 v181, v207, v211, s[8:9]
	v_cndmask_b32_e64 v138, v210, v206, s[8:9]
	v_cndmask_b32_e64 v139, v211, v207, s[8:9]
	s_mov_b64 s[26:27], 0x58000
	v_lshl_add_u64 v[204:205], v[6:7], 0, s[26:27]
	v_lshl_add_u64 v[206:207], v[204:205], 0, v[150:151]
	global_load_dwordx4 v[204:207], v[206:207], off
	s_mov_b64 s[26:27], 0x58000
	v_lshl_add_u64 v[208:209], v[6:7], 0, s[26:27]
	v_lshl_add_u64 v[208:209], v[208:209], 0, v[148:149]
	global_load_dwordx4 v[208:211], v[208:209], off
	v_mov_b32_dpp v182, v136 row_ror:8 row_mask:0xf bank_mask:0xf
	v_mov_b32_dpp v183, v137 row_ror:8 row_mask:0xf bank_mask:0xf
	v_lshlrev_b32_e32 v136, 16, v4
	v_and_b32_e32 v137, 0xffff0000, v4
	v_mov_b32_dpp v184, v138 row_ror:8 row_mask:0xf bank_mask:0xf
	v_mov_b32_dpp v185, v139 row_ror:8 row_mask:0xf bank_mask:0xf
	v_lshlrev_b32_e32 v138, 16, v179
	v_and_b32_e32 v139, 0xffff0000, v179
	v_lshlrev_b32_e32 v140, 16, v180
	v_and_b32_e32 v141, 0xffff0000, v180
	v_pk_mul_f32 v[116:117], v[116:117], v[136:137]
	v_lshlrev_b32_e32 v136, 16, v182
	v_and_b32_e32 v137, 0xffff0000, v182
	v_lshlrev_b32_e32 v142, 16, v181
	v_and_b32_e32 v143, 0xffff0000, v181
	v_pk_mul_f32 v[118:119], v[118:119], v[138:139]
	v_pk_mul_f32 v[112:113], v[112:113], v[140:141]
	v_lshlrev_b32_e32 v138, 16, v183
	v_and_b32_e32 v139, 0xffff0000, v183
	v_lshlrev_b32_e32 v140, 16, v184
	v_and_b32_e32 v141, 0xffff0000, v184
	v_pk_mul_f32 v[108:109], v[108:109], v[136:137]
	v_lshl_add_u64 v[136:137], v[6:7], 0, s[26:27]
	v_pk_mul_f32 v[114:115], v[114:115], v[142:143]
	v_lshlrev_b32_e32 v142, 16, v185
	v_and_b32_e32 v143, 0xffff0000, v185
	v_pk_mul_f32 v[110:111], v[110:111], v[138:139]
	v_pk_mul_f32 v[104:105], v[104:105], v[140:141]
	v_lshl_add_u64 v[138:139], v[136:137], 0, v[148:149]
	v_lshl_add_u64 v[140:141], v[136:137], 0, v[150:151]
	v_pk_mul_f32 v[106:107], v[106:107], v[142:143]
	v_mov_b32_e32 v184, v5
	v_mov_b32_e32 v182, v5
	v_mov_b32_e32 v183, v5
	v_mov_b32_e32 v185, v5
	s_mov_b64 s[26:27], 0x40000
	s_waitcnt vmcnt(10)
	v_cndmask_b32_e64 v180, v218, v214, s[8:9]
	v_cndmask_b32_e64 v138, v214, v218, s[8:9]
	v_cndmask_b32_e64 v4, v216, v212, s[8:9]
	v_cndmask_b32_e64 v179, v217, v213, s[8:9]
	v_cndmask_b32_e64 v136, v212, v216, s[8:9]
	v_cndmask_b32_e64 v137, v213, v217, s[8:9]
	v_mov_b32_dpp v184, v138 row_ror:8 row_mask:0xf bank_mask:0xf
	v_lshlrev_b32_e32 v140, 16, v180
	v_and_b32_e32 v141, 0xffff0000, v180
	v_cndmask_b32_e64 v181, v219, v215, s[8:9]
	v_cndmask_b32_e64 v139, v215, v219, s[8:9]
	v_mov_b32_dpp v182, v136 row_ror:8 row_mask:0xf bank_mask:0xf
	v_mov_b32_dpp v183, v137 row_ror:8 row_mask:0xf bank_mask:0xf
	v_lshlrev_b32_e32 v136, 16, v4
	v_and_b32_e32 v137, 0xffff0000, v4
	v_pk_mul_f32 v[96:97], v[96:97], v[140:141]
	v_lshlrev_b32_e32 v140, 16, v184
	v_and_b32_e32 v141, 0xffff0000, v184
	v_mov_b32_dpp v185, v139 row_ror:8 row_mask:0xf bank_mask:0xf
	v_lshlrev_b32_e32 v138, 16, v179
	v_and_b32_e32 v139, 0xffff0000, v179
	v_lshlrev_b32_e32 v142, 16, v181
	v_and_b32_e32 v143, 0xffff0000, v181
	v_pk_mul_f32 v[100:101], v[100:101], v[136:137]
	v_lshlrev_b32_e32 v136, 16, v182
	v_and_b32_e32 v137, 0xffff0000, v182
	v_pk_mul_f32 v[88:89], v[88:89], v[140:141]
	v_lshl_add_u64 v[140:141], v[6:7], 0, s[14:15]
	v_pk_mul_f32 v[102:103], v[102:103], v[138:139]
	v_pk_mul_f32 v[98:99], v[98:99], v[142:143]
	v_lshlrev_b32_e32 v138, 16, v183
	v_and_b32_e32 v139, 0xffff0000, v183
	v_lshlrev_b32_e32 v142, 16, v185
	v_and_b32_e32 v143, 0xffff0000, v185
	v_pk_mul_f32 v[92:93], v[92:93], v[136:137]
	v_lshl_add_u64 v[136:137], v[140:141], 0, v[150:151]
	v_lshl_add_u64 v[140:141], v[140:141], 0, v[148:149]
	v_pk_mul_f32 v[94:95], v[94:95], v[138:139]
	v_pk_mul_f32 v[90:91], v[90:91], v[142:143]
	v_mov_b32_e32 v182, v5
	v_mov_b32_e32 v183, v5
	v_mov_b32_e32 v184, v5
	v_mov_b32_e32 v185, v5
	s_waitcnt vmcnt(8)
	v_cndmask_b32_e64 v4, v220, v224, s[8:9]
	v_cndmask_b32_e64 v179, v221, v225, s[8:9]
	v_cndmask_b32_e64 v136, v224, v220, s[8:9]
	v_cndmask_b32_e64 v137, v225, v221, s[8:9]
	v_cndmask_b32_e64 v180, v222, v226, s[8:9]
	v_cndmask_b32_e64 v181, v223, v227, s[8:9]
	v_cndmask_b32_e64 v138, v226, v222, s[8:9]
	v_cndmask_b32_e64 v139, v227, v223, s[8:9]
	v_mov_b32_dpp v182, v136 row_ror:8 row_mask:0xf bank_mask:0xf
	v_mov_b32_dpp v183, v137 row_ror:8 row_mask:0xf bank_mask:0xf
	v_lshlrev_b32_e32 v136, 16, v4
	v_and_b32_e32 v137, 0xffff0000, v4
	v_mov_b32_dpp v184, v138 row_ror:8 row_mask:0xf bank_mask:0xf
	v_mov_b32_dpp v185, v139 row_ror:8 row_mask:0xf bank_mask:0xf
	v_lshlrev_b32_e32 v138, 16, v179
	v_and_b32_e32 v139, 0xffff0000, v179
	v_lshlrev_b32_e32 v140, 16, v180
	v_and_b32_e32 v141, 0xffff0000, v180
	v_pk_mul_f32 v[84:85], v[84:85], v[136:137]
	v_lshlrev_b32_e32 v136, 16, v182
	v_and_b32_e32 v137, 0xffff0000, v182
	v_lshlrev_b32_e32 v142, 16, v181
	v_and_b32_e32 v143, 0xffff0000, v181
	v_pk_mul_f32 v[86:87], v[86:87], v[138:139]
	v_pk_mul_f32 v[80:81], v[80:81], v[140:141]
	v_lshlrev_b32_e32 v138, 16, v183
	v_and_b32_e32 v139, 0xffff0000, v183
	v_lshlrev_b32_e32 v140, 16, v184
	v_and_b32_e32 v141, 0xffff0000, v184
	v_pk_mul_f32 v[76:77], v[76:77], v[136:137]
	v_lshl_add_u64 v[136:137], v[6:7], 0, s[26:27]
	v_pk_mul_f32 v[82:83], v[82:83], v[142:143]
	v_lshlrev_b32_e32 v142, 16, v185
	v_and_b32_e32 v143, 0xffff0000, v185
	v_pk_mul_f32 v[78:79], v[78:79], v[138:139]
	v_pk_mul_f32 v[72:73], v[72:73], v[140:141]
	v_lshl_add_u64 v[138:139], v[136:137], 0, v[148:149]
	v_lshl_add_u64 v[140:141], v[136:137], 0, v[150:151]
	v_pk_mul_f32 v[74:75], v[74:75], v[142:143]
	v_mov_b32_e32 v184, v5
	v_mov_b32_e32 v182, v5
	v_mov_b32_e32 v183, v5
	v_mov_b32_e32 v185, v5
	s_mov_b64 s[26:27], 0x48000
	s_waitcnt vmcnt(6)
	v_cndmask_b32_e64 v180, v234, v230, s[8:9]
	v_cndmask_b32_e64 v138, v230, v234, s[8:9]
	v_cndmask_b32_e64 v4, v232, v228, s[8:9]
	v_cndmask_b32_e64 v179, v233, v229, s[8:9]
	v_cndmask_b32_e64 v136, v228, v232, s[8:9]
	v_cndmask_b32_e64 v137, v229, v233, s[8:9]
	v_mov_b32_dpp v184, v138 row_ror:8 row_mask:0xf bank_mask:0xf
	v_lshlrev_b32_e32 v140, 16, v180
	v_and_b32_e32 v141, 0xffff0000, v180
	v_cndmask_b32_e64 v181, v235, v231, s[8:9]
	v_cndmask_b32_e64 v139, v231, v235, s[8:9]
	v_mov_b32_dpp v182, v136 row_ror:8 row_mask:0xf bank_mask:0xf
	v_mov_b32_dpp v183, v137 row_ror:8 row_mask:0xf bank_mask:0xf
	v_lshlrev_b32_e32 v136, 16, v4
	v_and_b32_e32 v137, 0xffff0000, v4
	v_pk_mul_f32 v[64:65], v[64:65], v[140:141]
	v_lshlrev_b32_e32 v140, 16, v184
	v_and_b32_e32 v141, 0xffff0000, v184
	v_mov_b32_dpp v185, v139 row_ror:8 row_mask:0xf bank_mask:0xf
	v_lshlrev_b32_e32 v138, 16, v179
	v_and_b32_e32 v139, 0xffff0000, v179
	v_lshlrev_b32_e32 v142, 16, v181
	v_and_b32_e32 v143, 0xffff0000, v181
	v_pk_mul_f32 v[68:69], v[68:69], v[136:137]
	v_lshlrev_b32_e32 v136, 16, v182
	v_and_b32_e32 v137, 0xffff0000, v182
	v_pk_mul_f32 v[56:57], v[56:57], v[140:141]
	v_lshl_add_u64 v[140:141], v[6:7], 0, s[26:27]
	v_pk_mul_f32 v[70:71], v[70:71], v[138:139]
	v_pk_mul_f32 v[66:67], v[66:67], v[142:143]
	v_lshlrev_b32_e32 v138, 16, v183
	v_and_b32_e32 v139, 0xffff0000, v183
	v_lshlrev_b32_e32 v142, 16, v185
	v_and_b32_e32 v143, 0xffff0000, v185
	v_pk_mul_f32 v[60:61], v[60:61], v[136:137]
	v_lshl_add_u64 v[136:137], v[140:141], 0, v[150:151]
	v_lshl_add_u64 v[140:141], v[140:141], 0, v[148:149]
	v_pk_mul_f32 v[62:63], v[62:63], v[138:139]
	v_pk_mul_f32 v[58:59], v[58:59], v[142:143]
	v_mov_b32_e32 v182, v5
	v_mov_b32_e32 v183, v5
	v_mov_b32_e32 v184, v5
	v_mov_b32_e32 v185, v5
	s_mov_b64 s[26:27], 0x50000
	s_waitcnt vmcnt(4)
	v_cndmask_b32_e64 v4, v236, v240, s[8:9]
	v_cndmask_b32_e64 v179, v237, v241, s[8:9]
	v_cndmask_b32_e64 v136, v240, v236, s[8:9]
	v_cndmask_b32_e64 v137, v241, v237, s[8:9]
	v_cndmask_b32_e64 v180, v238, v242, s[8:9]
	v_cndmask_b32_e64 v181, v239, v243, s[8:9]
	v_cndmask_b32_e64 v138, v242, v238, s[8:9]
	v_cndmask_b32_e64 v139, v243, v239, s[8:9]
	v_mov_b32_dpp v182, v136 row_ror:8 row_mask:0xf bank_mask:0xf
	v_mov_b32_dpp v183, v137 row_ror:8 row_mask:0xf bank_mask:0xf
	v_lshlrev_b32_e32 v136, 16, v4
	v_and_b32_e32 v137, 0xffff0000, v4
	v_mov_b32_dpp v184, v138 row_ror:8 row_mask:0xf bank_mask:0xf
	v_mov_b32_dpp v185, v139 row_ror:8 row_mask:0xf bank_mask:0xf
	v_lshlrev_b32_e32 v138, 16, v179
	v_and_b32_e32 v139, 0xffff0000, v179
	v_lshlrev_b32_e32 v140, 16, v180
	v_and_b32_e32 v141, 0xffff0000, v180
	v_pk_mul_f32 v[52:53], v[52:53], v[136:137]
	v_lshlrev_b32_e32 v136, 16, v182
	v_and_b32_e32 v137, 0xffff0000, v182
	v_lshlrev_b32_e32 v142, 16, v181
	v_and_b32_e32 v143, 0xffff0000, v181
	v_pk_mul_f32 v[54:55], v[54:55], v[138:139]
	v_pk_mul_f32 v[48:49], v[48:49], v[140:141]
	v_lshlrev_b32_e32 v138, 16, v183
	v_and_b32_e32 v139, 0xffff0000, v183
	v_lshlrev_b32_e32 v140, 16, v184
	v_and_b32_e32 v141, 0xffff0000, v184
	v_pk_mul_f32 v[44:45], v[44:45], v[136:137]
	v_lshl_add_u64 v[136:137], v[6:7], 0, s[26:27]
	v_pk_mul_f32 v[50:51], v[50:51], v[142:143]
	v_lshlrev_b32_e32 v142, 16, v185
	v_and_b32_e32 v143, 0xffff0000, v185
	v_pk_mul_f32 v[46:47], v[46:47], v[138:139]
	v_pk_mul_f32 v[40:41], v[40:41], v[140:141]
	v_lshl_add_u64 v[138:139], v[136:137], 0, v[148:149]
	v_lshl_add_u64 v[140:141], v[136:137], 0, v[150:151]
	v_pk_mul_f32 v[42:43], v[42:43], v[142:143]
	v_mov_b32_e32 v182, v5
	v_mov_b32_e32 v183, v5
	v_mov_b32_e32 v184, v5
	v_mov_b32_e32 v185, v5
	s_mov_b64 s[26:27], 0x58000
	v_lshl_add_u64 v[6:7], v[6:7], 0, s[26:27]
	s_waitcnt vmcnt(2)
	v_cndmask_b32_e64 v4, v200, v196, s[8:9]
	v_cndmask_b32_e64 v179, v201, v197, s[8:9]
	v_cndmask_b32_e64 v136, v196, v200, s[8:9]
	v_cndmask_b32_e64 v137, v197, v201, s[8:9]
	v_cndmask_b32_e64 v180, v202, v198, s[8:9]
	v_cndmask_b32_e64 v181, v203, v199, s[8:9]
	v_cndmask_b32_e64 v138, v198, v202, s[8:9]
	v_cndmask_b32_e64 v139, v199, v203, s[8:9]
	v_mov_b32_dpp v182, v136 row_ror:8 row_mask:0xf bank_mask:0xf
	v_mov_b32_dpp v183, v137 row_ror:8 row_mask:0xf bank_mask:0xf
	v_lshlrev_b32_e32 v136, 16, v4
	v_and_b32_e32 v137, 0xffff0000, v4
	v_mov_b32_dpp v184, v138 row_ror:8 row_mask:0xf bank_mask:0xf
	v_mov_b32_dpp v185, v139 row_ror:8 row_mask:0xf bank_mask:0xf
	v_lshlrev_b32_e32 v138, 16, v179
	v_and_b32_e32 v139, 0xffff0000, v179
	v_lshlrev_b32_e32 v140, 16, v180
	v_and_b32_e32 v141, 0xffff0000, v180
	v_lshlrev_b32_e32 v142, 16, v181
	v_and_b32_e32 v143, 0xffff0000, v181
	v_pk_mul_f32 v[36:37], v[36:37], v[136:137]
	v_lshlrev_b32_e32 v136, 16, v182
	v_and_b32_e32 v137, 0xffff0000, v182
	v_pk_mul_f32 v[38:39], v[38:39], v[138:139]
	v_pk_mul_f32 v[34:35], v[34:35], v[142:143]
	v_pk_mul_f32 v[32:33], v[32:33], v[140:141]
	v_lshlrev_b32_e32 v138, 16, v183
	v_and_b32_e32 v139, 0xffff0000, v183
	v_lshlrev_b32_e32 v140, 16, v184
	v_and_b32_e32 v141, 0xffff0000, v184
	v_lshlrev_b32_e32 v142, 16, v185
	v_and_b32_e32 v143, 0xffff0000, v185
	v_pk_mul_f32 v[28:29], v[28:29], v[136:137]
	v_lshl_add_u64 v[136:137], v[6:7], 0, v[150:151]
	v_lshl_add_u64 v[6:7], v[6:7], 0, v[148:149]
	v_pk_mul_f32 v[30:31], v[30:31], v[138:139]
	v_pk_mul_f32 v[26:27], v[26:27], v[142:143]
	v_pk_mul_f32 v[24:25], v[24:25], v[140:141]
	v_mov_b32_e32 v182, v5
	v_mov_b32_e32 v183, v5
	s_waitcnt vmcnt(0)
	v_cndmask_b32_e64 v4, v204, v208, s[8:9]
	v_cndmask_b32_e64 v179, v205, v209, s[8:9]
	v_cndmask_b32_e64 v180, v206, v210, s[8:9]
	v_cndmask_b32_e64 v181, v207, v211, s[8:9]
	v_cndmask_b32_e64 v6, v208, v204, s[8:9]
	v_cndmask_b32_e64 v7, v209, v205, s[8:9]
	v_cndmask_b32_e64 v136, v210, v206, s[8:9]
	v_cndmask_b32_e64 v137, v211, v207, s[8:9]
	v_mov_b32_e32 v142, v5
	v_mov_b32_e32 v143, v5
	v_mov_b32_dpp v182, v136 row_ror:8 row_mask:0xf bank_mask:0xf
	v_mov_b32_dpp v142, v6 row_ror:8 row_mask:0xf bank_mask:0xf
	v_mov_b32_dpp v143, v7 row_ror:8 row_mask:0xf bank_mask:0xf
	v_mov_b32_dpp v183, v137 row_ror:8 row_mask:0xf bank_mask:0xf
	v_lshlrev_b32_e32 v6, 16, v4
	v_and_b32_e32 v7, 0xffff0000, v4
	v_lshlrev_b32_e32 v136, 16, v179
	v_and_b32_e32 v137, 0xffff0000, v179
	v_lshlrev_b32_e32 v138, 16, v180
	v_and_b32_e32 v139, 0xffff0000, v180
	v_lshlrev_b32_e32 v140, 16, v181
	v_and_b32_e32 v141, 0xffff0000, v181
	v_pk_mul_f32 v[22:23], v[22:23], v[136:137]
	v_pk_mul_f32 v[20:21], v[20:21], v[6:7]
	v_pk_mul_f32 v[18:19], v[18:19], v[140:141]
	v_pk_mul_f32 v[16:17], v[16:17], v[138:139]
	v_lshlrev_b32_e32 v6, 16, v142
	v_and_b32_e32 v7, 0xffff0000, v142
	v_lshlrev_b32_e32 v136, 16, v143
	v_and_b32_e32 v137, 0xffff0000, v143
	v_lshlrev_b32_e32 v138, 16, v182
	v_and_b32_e32 v139, 0xffff0000, v182
	v_lshlrev_b32_e32 v140, 16, v183
	v_and_b32_e32 v141, 0xffff0000, v183
	v_pk_mul_f32 v[14:15], v[14:15], v[136:137]
	v_pk_mul_f32 v[12:13], v[12:13], v[6:7]
	v_pk_mul_f32 v[10:11], v[10:11], v[140:141]
	v_pk_mul_f32 v[8:9], v[8:9], v[138:139]
	s_branch .LBB0_779

.LBB0_784:
	v_lshl_add_u32 v136, s91, 8, v1
	v_or_b32_e32 v6, s92, v174
	v_ashrrev_i32_e32 v137, 31, v136
	v_ashrrev_i32_e32 v7, 31, v6
	v_lshlrev_b64 v[196:197], 10, v[136:137]
	v_lshl_add_u64 v[196:197], v[196:197], 0, v[6:7]
	v_lshlrev_b64 v[198:199], 1, v[196:197]
	v_lshl_add_u64 v[196:197], s[46:47], 0, v[198:199]
	v_lshl_add_u64 v[244:245], v[196:197], 0, v[148:149]
	global_load_dwordx4 v[196:199], v[244:245], off
	v_lshlrev_b64 v[200:201], 10, v[136:137]
	v_lshl_add_u64 v[200:201], v[200:201], 0, v[6:7]
	v_lshlrev_b64 v[202:203], 1, v[200:201]
	v_lshl_add_u64 v[200:201], s[46:47], 0, v[202:203]
	v_lshl_add_u64 v[244:245], v[200:201], 0, v[150:151]
	global_load_dwordx4 v[200:203], v[244:245], off
	v_or_b32_e32 v204, 16, v136
	v_ashrrev_i32_e32 v205, 31, v204
	v_lshlrev_b64 v[204:205], 10, v[204:205]
	v_lshl_add_u64 v[204:205], v[204:205], 0, v[6:7]
	v_lshlrev_b64 v[206:207], 1, v[204:205]
	v_lshl_add_u64 v[204:205], s[46:47], 0, v[206:207]
	v_lshl_add_u64 v[244:245], v[204:205], 0, v[148:149]
	global_load_dwordx4 v[204:207], v[244:245], off
	v_or_b32_e32 v208, 16, v136
	v_ashrrev_i32_e32 v209, 31, v208
	v_lshlrev_b64 v[208:209], 10, v[208:209]
	v_lshl_add_u64 v[208:209], v[208:209], 0, v[6:7]
	v_lshlrev_b64 v[210:211], 1, v[208:209]
	v_lshl_add_u64 v[208:209], s[46:47], 0, v[210:211]
	v_lshl_add_u64 v[244:245], v[208:209], 0, v[150:151]
	global_load_dwordx4 v[208:211], v[244:245], off
	v_or_b32_e32 v212, 32, v136
	v_ashrrev_i32_e32 v213, 31, v212
	v_lshlrev_b64 v[212:213], 10, v[212:213]
	v_lshl_add_u64 v[212:213], v[212:213], 0, v[6:7]
	v_lshlrev_b64 v[214:215], 1, v[212:213]
	v_lshl_add_u64 v[212:213], s[46:47], 0, v[214:215]
	v_lshl_add_u64 v[244:245], v[212:213], 0, v[148:149]
	global_load_dwordx4 v[212:215], v[244:245], off
	v_or_b32_e32 v216, 32, v136
	v_ashrrev_i32_e32 v217, 31, v216
	v_lshlrev_b64 v[216:217], 10, v[216:217]
	v_lshl_add_u64 v[216:217], v[216:217], 0, v[6:7]
	v_lshlrev_b64 v[218:219], 1, v[216:217]
	v_lshl_add_u64 v[216:217], s[46:47], 0, v[218:219]
	v_lshl_add_u64 v[244:245], v[216:217], 0, v[150:151]
	global_load_dwordx4 v[216:219], v[244:245], off
	v_or_b32_e32 v220, 48, v136
	v_ashrrev_i32_e32 v221, 31, v220
	v_lshlrev_b64 v[220:221], 10, v[220:221]
	v_lshl_add_u64 v[220:221], v[220:221], 0, v[6:7]
	v_lshlrev_b64 v[222:223], 1, v[220:221]
	v_lshl_add_u64 v[220:221], s[46:47], 0, v[222:223]
	v_lshl_add_u64 v[244:245], v[220:221], 0, v[148:149]
	global_load_dwordx4 v[220:223], v[244:245], off
	v_or_b32_e32 v224, 48, v136
	v_ashrrev_i32_e32 v225, 31, v224
	v_lshlrev_b64 v[224:225], 10, v[224:225]
	v_lshl_add_u64 v[224:225], v[224:225], 0, v[6:7]
	v_lshlrev_b64 v[226:227], 1, v[224:225]
	v_lshl_add_u64 v[224:225], s[46:47], 0, v[226:227]
	v_lshl_add_u64 v[244:245], v[224:225], 0, v[150:151]
	global_load_dwordx4 v[224:227], v[244:245], off
	v_lshlrev_b64 v[228:229], 10, v[136:137]
	v_lshl_add_u64 v[228:229], v[228:229], 0, v[6:7]
	v_lshl_add_u64 v[230:231], v[228:229], 1, v[162:163]
	v_lshl_add_u64 v[244:245], s[46:47], 0, v[230:231]
	v_lshl_add_u64 v[246:247], v[244:245], 0, v[148:149]
	global_load_dwordx4 v[228:231], v[246:247], off
	v_lshlrev_b64 v[232:233], 10, v[136:137]
	v_lshl_add_u64 v[232:233], v[232:233], 0, v[6:7]
	v_lshl_add_u64 v[234:235], v[232:233], 1, v[162:163]
	v_lshl_add_u64 v[244:245], s[46:47], 0, v[234:235]
	v_lshl_add_u64 v[246:247], v[244:245], 0, v[150:151]
	global_load_dwordx4 v[232:235], v[246:247], off
	v_lshlrev_b64 v[236:237], 10, v[136:137]
	v_lshl_add_u64 v[236:237], v[236:237], 0, v[6:7]
	v_lshl_add_u64 v[238:239], v[236:237], 1, v[164:165]
	v_lshl_add_u64 v[244:245], s[46:47], 0, v[238:239]
	v_lshl_add_u64 v[246:247], v[244:245], 0, v[148:149]
	global_load_dwordx4 v[236:239], v[246:247], off
	v_lshlrev_b64 v[240:241], 10, v[136:137]
	v_lshl_add_u64 v[240:241], v[240:241], 0, v[6:7]
	v_lshl_add_u64 v[242:243], v[240:241], 1, v[164:165]
	v_lshl_add_u64 v[244:245], s[46:47], 0, v[242:243]
	v_lshl_add_u64 v[246:247], v[244:245], 0, v[150:151]
	global_load_dwordx4 v[240:243], v[246:247], off
	v_lshlrev_b64 v[138:139], 10, v[136:137]
	v_lshl_add_u64 v[138:139], v[138:139], 0, v[6:7]
	v_lshlrev_b64 v[142:143], 1, v[138:139]
	v_lshl_add_u64 v[138:139], s[46:47], 0, v[142:143]
	v_lshl_add_u64 v[140:141], v[138:139], 0, v[148:149]
	v_lshl_add_u64 v[170:171], v[138:139], 0, v[150:151]
	v_mov_b32_e32 v183, v5
	v_mov_b32_e32 v184, v5
	s_waitcnt vmcnt(10)
	v_cndmask_b32_e64 v4, v200, v196, s[8:9]
	v_cndmask_b32_e64 v170, v201, v197, s[8:9]
	v_cndmask_b32_e64 v171, v202, v198, s[8:9]
	v_cndmask_b32_e64 v182, v203, v199, s[8:9]
	v_cndmask_b32_e64 v138, v196, v200, s[8:9]
	v_cndmask_b32_e64 v139, v197, v201, s[8:9]
	v_cndmask_b32_e64 v140, v198, v202, s[8:9]
	v_cndmask_b32_e64 v141, v199, v203, s[8:9]
	v_lshlrev_b64 v[196:197], 10, v[136:137]
	v_lshl_add_u64 v[198:199], v[196:197], 0, v[6:7]
	v_lshl_add_u64 v[244:245], v[198:199], 1, v[166:167]
	v_lshl_add_u64 v[196:197], s[46:47], 0, v[244:245]
	v_lshl_add_u64 v[246:247], v[196:197], 0, v[148:149]
	global_load_dwordx4 v[196:199], v[246:247], off
	v_lshlrev_b64 v[200:201], 10, v[136:137]
	v_lshl_add_u64 v[202:203], v[200:201], 0, v[6:7]
	v_lshl_add_u64 v[244:245], v[202:203], 1, v[166:167]
	v_lshl_add_u64 v[200:201], s[46:47], 0, v[244:245]
	v_lshl_add_u64 v[246:247], v[200:201], 0, v[150:151]
	global_load_dwordx4 v[200:203], v[246:247], off
	v_mov_b32_e32 v180, v5
	v_mov_b32_e32 v181, v5
	v_mov_b32_dpp v183, v140 row_ror:8 row_mask:0xf bank_mask:0xf
	v_mov_b32_dpp v180, v138 row_ror:8 row_mask:0xf bank_mask:0xf
	v_mov_b32_dpp v181, v139 row_ror:8 row_mask:0xf bank_mask:0xf
	v_mov_b32_dpp v184, v141 row_ror:8 row_mask:0xf bank_mask:0xf
	v_lshlrev_b32_e32 v138, 16, v4
	v_and_b32_e32 v139, 0xffff0000, v4
	v_lshlrev_b32_e32 v140, 16, v170
	v_and_b32_e32 v141, 0xffff0000, v170
	v_lshlrev_b32_e32 v170, 16, v171
	v_and_b32_e32 v171, 0xffff0000, v171
	v_lshlrev_b32_e32 v178, 16, v182
	v_and_b32_e32 v179, 0xffff0000, v182
	v_pk_mul_f32 v[134:135], v[134:135], v[140:141]
	v_pk_mul_f32 v[132:133], v[132:133], v[138:139]
	v_pk_mul_f32 v[130:131], v[130:131], v[178:179]
	v_pk_mul_f32 v[128:129], v[128:129], v[170:171]
	v_cvt_pk_bf16_f32 v4, v132, v133
	v_cvt_pk_bf16_f32 v132, v134, v135
	v_lshlrev_b32_e32 v138, 16, v183
	v_cvt_pk_bf16_f32 v133, v128, v129
	v_cvt_pk_bf16_f32 v134, v130, v131
	v_lshlrev_b32_e32 v128, 16, v180
	v_and_b32_e32 v129, 0xffff0000, v180
	v_lshlrev_b32_e32 v130, 16, v181
	v_and_b32_e32 v131, 0xffff0000, v181
	v_and_b32_e32 v139, 0xffff0000, v183
	v_lshlrev_b32_e32 v140, 16, v184
	v_and_b32_e32 v141, 0xffff0000, v184
	v_pk_mul_f32 v[126:127], v[126:127], v[130:131]
	v_pk_mul_f32 v[124:125], v[124:125], v[128:129]
	v_pk_mul_f32 v[122:123], v[122:123], v[140:141]
	v_pk_mul_f32 v[120:121], v[120:121], v[138:139]
	v_cvt_pk_bf16_f32 v124, v124, v125
	v_cvt_pk_bf16_f32 v125, v126, v127
	v_lshl_add_u64 v[128:129], s[40:41], 0, v[142:143]
	v_cvt_pk_bf16_f32 v126, v120, v121
	v_cvt_pk_bf16_f32 v127, v122, v123
	v_mov_b32_e32 v120, v5
	v_mov_b32_e32 v121, v5
	v_mov_b32_e32 v122, v5
	v_mov_b32_e32 v123, v5
	v_mov_b32_dpp v120, v124 row_ror:8 row_mask:0xf bank_mask:0xf
	v_mov_b32_dpp v121, v125 row_ror:8 row_mask:0xf bank_mask:0xf
	v_mov_b32_dpp v122, v126 row_ror:8 row_mask:0xf bank_mask:0xf
	v_mov_b32_dpp v123, v127 row_ror:8 row_mask:0xf bank_mask:0xf
	v_lshl_add_u64 v[130:131], v[128:129], 0, s[58:59]
	v_mov_b32_e32 v124, v4
	v_mov_b32_e32 v125, v132
	v_mov_b32_e32 v126, v133
	v_mov_b32_e32 v127, v134
	s_and_saveexec_b64 s[26:27], s[8:9]
	s_cbranch_execz .LBB0_786
	v_lshl_add_u64 v[138:139], v[128:129], 0, s[60:61]
	v_mov_b64_e32 v[130:131], v[128:129]
	v_mov_b32_e32 v124, v120
	v_mov_b32_e32 v125, v121
	v_mov_b32_e32 v126, v122
	v_mov_b32_e32 v127, v123
	v_mov_b32_e32 v120, v4
	v_mov_b32_e32 v121, v132
	v_mov_b32_e32 v122, v133
	v_mov_b32_e32 v123, v134
	v_mov_b64_e32 v[128:129], v[138:139]
.LBB0_786:
	s_or_b64 exec, exec, s[26:27]
	global_store_dwordx4 v[130:131], v[120:123], off
	global_store_dwordx4 v[128:129], v[124:127], off
	v_mov_b32_e32 v133, v5
	v_or_b32_e32 v120, 16, v136
	v_ashrrev_i32_e32 v121, 31, v120
	v_lshlrev_b64 v[120:121], 10, v[120:121]
	v_lshl_add_u64 v[120:121], v[120:121], 0, v[6:7]
	v_lshlrev_b64 v[128:129], 1, v[120:121]
	v_lshl_add_u64 v[120:121], s[46:47], 0, v[128:129]
	v_lshl_add_u64 v[122:123], v[120:121], 0, v[148:149]
	v_lshl_add_u64 v[124:125], v[120:121], 0, v[150:151]
	v_mov_b32_e32 v134, v5
	v_mov_b32_e32 v135, v5
	v_mov_b32_e32 v138, v5
	s_waitcnt vmcnt(12)
	v_cndmask_b32_e64 v4, v208, v204, s[8:9]
	v_cndmask_b32_e64 v130, v209, v205, s[8:9]
	v_cndmask_b32_e64 v131, v210, v206, s[8:9]
	v_cndmask_b32_e64 v132, v211, v207, s[8:9]
	v_cndmask_b32_e64 v120, v204, v208, s[8:9]
	v_cndmask_b32_e64 v121, v205, v209, s[8:9]
	v_cndmask_b32_e64 v122, v206, v210, s[8:9]
	v_cndmask_b32_e64 v123, v207, v211, s[8:9]
	v_lshlrev_b64 v[204:205], 10, v[136:137]
	v_lshl_add_u64 v[206:207], v[204:205], 0, v[6:7]
	v_lshl_add_u64 v[206:207], v[206:207], 1, v[168:169]
	v_lshl_add_u64 v[244:245], s[46:47], 0, v[206:207]
	v_lshl_add_u64 v[246:247], v[244:245], 0, v[148:149]
	global_load_dwordx4 v[204:207], v[246:247], off
	v_lshlrev_b64 v[208:209], 10, v[136:137]
	v_lshl_add_u64 v[210:211], v[208:209], 0, v[6:7]
	v_lshl_add_u64 v[210:211], v[210:211], 1, v[168:169]
	v_lshl_add_u64 v[244:245], s[46:47], 0, v[210:211]
	v_lshl_add_u64 v[246:247], v[244:245], 0, v[150:151]
	global_load_dwordx4 v[208:211], v[246:247], off
	v_mov_b32_dpp v133, v120 row_ror:8 row_mask:0xf bank_mask:0xf
	v_mov_b32_dpp v134, v121 row_ror:8 row_mask:0xf bank_mask:0xf
	v_mov_b32_dpp v135, v122 row_ror:8 row_mask:0xf bank_mask:0xf
	v_mov_b32_dpp v138, v123 row_ror:8 row_mask:0xf bank_mask:0xf
	v_lshlrev_b32_e32 v120, 16, v4
	v_and_b32_e32 v121, 0xffff0000, v4
	v_lshlrev_b32_e32 v122, 16, v130
	v_and_b32_e32 v123, 0xffff0000, v130
	v_lshlrev_b32_e32 v124, 16, v131
	v_and_b32_e32 v125, 0xffff0000, v131
	v_lshlrev_b32_e32 v126, 16, v132
	v_and_b32_e32 v127, 0xffff0000, v132
	v_pk_mul_f32 v[118:119], v[118:119], v[122:123]
	v_pk_mul_f32 v[116:117], v[116:117], v[120:121]
	v_pk_mul_f32 v[114:115], v[114:115], v[126:127]
	v_pk_mul_f32 v[112:113], v[112:113], v[124:125]
	v_cvt_pk_bf16_f32 v4, v116, v117
	v_cvt_pk_bf16_f32 v116, v118, v119
	v_lshlrev_b32_e32 v120, 16, v135
	v_cvt_pk_bf16_f32 v117, v112, v113
	v_cvt_pk_bf16_f32 v118, v114, v115
	v_lshlrev_b32_e32 v112, 16, v133
	v_and_b32_e32 v113, 0xffff0000, v133
	v_lshlrev_b32_e32 v114, 16, v134
	v_and_b32_e32 v115, 0xffff0000, v134
	v_and_b32_e32 v121, 0xffff0000, v135
	v_lshlrev_b32_e32 v122, 16, v138
	v_and_b32_e32 v123, 0xffff0000, v138
	v_pk_mul_f32 v[110:111], v[110:111], v[114:115]
	v_pk_mul_f32 v[108:109], v[108:109], v[112:113]
	v_pk_mul_f32 v[106:107], v[106:107], v[122:123]
	v_pk_mul_f32 v[104:105], v[104:105], v[120:121]
	v_cvt_pk_bf16_f32 v108, v108, v109
	v_cvt_pk_bf16_f32 v109, v110, v111
	v_lshl_add_u64 v[112:113], s[40:41], 0, v[128:129]
	v_cvt_pk_bf16_f32 v110, v104, v105
	v_cvt_pk_bf16_f32 v111, v106, v107
	v_mov_b32_e32 v104, v5
	v_mov_b32_e32 v105, v5
	v_mov_b32_e32 v106, v5
	v_mov_b32_e32 v107, v5
	v_mov_b32_dpp v104, v108 row_ror:8 row_mask:0xf bank_mask:0xf
	v_mov_b32_dpp v105, v109 row_ror:8 row_mask:0xf bank_mask:0xf
	v_mov_b32_dpp v106, v110 row_ror:8 row_mask:0xf bank_mask:0xf
	v_mov_b32_dpp v107, v111 row_ror:8 row_mask:0xf bank_mask:0xf
	v_lshl_add_u64 v[114:115], v[112:113], 0, s[58:59]
	v_mov_b32_e32 v108, v4
	v_mov_b32_e32 v109, v116
	v_mov_b32_e32 v110, v117
	v_mov_b32_e32 v111, v118
	s_and_saveexec_b64 s[26:27], s[8:9]
	s_cbranch_execz .LBB0_788
	v_lshl_add_u64 v[120:121], v[112:113], 0, s[60:61]
	v_mov_b64_e32 v[114:115], v[112:113]
	v_mov_b32_e32 v108, v104
	v_mov_b32_e32 v109, v105
	v_mov_b32_e32 v110, v106
	v_mov_b32_e32 v111, v107
	v_mov_b32_e32 v104, v4
	v_mov_b32_e32 v105, v116
	v_mov_b32_e32 v106, v117
	v_mov_b32_e32 v107, v118
	v_mov_b64_e32 v[112:113], v[120:121]
.LBB0_788:
	s_or_b64 exec, exec, s[26:27]
	global_store_dwordx4 v[114:115], v[104:107], off
	global_store_dwordx4 v[112:113], v[108:111], off
	v_mov_b32_e32 v117, v5
	v_or_b32_e32 v104, 32, v136
	v_ashrrev_i32_e32 v105, 31, v104
	v_lshlrev_b64 v[104:105], 10, v[104:105]
	v_lshl_add_u64 v[104:105], v[104:105], 0, v[6:7]
	v_lshlrev_b64 v[112:113], 1, v[104:105]
	v_lshl_add_u64 v[104:105], s[46:47], 0, v[112:113]
	v_lshl_add_u64 v[106:107], v[104:105], 0, v[148:149]
	v_lshl_add_u64 v[108:109], v[104:105], 0, v[150:151]
	v_mov_b32_e32 v118, v5
	v_mov_b32_e32 v119, v5
	v_mov_b32_e32 v120, v5
	s_waitcnt vmcnt(14)
	v_cndmask_b32_e64 v4, v216, v212, s[8:9]
	v_cndmask_b32_e64 v114, v217, v213, s[8:9]
	v_cndmask_b32_e64 v115, v218, v214, s[8:9]
	v_cndmask_b32_e64 v116, v219, v215, s[8:9]
	v_cndmask_b32_e64 v104, v212, v216, s[8:9]
	v_cndmask_b32_e64 v105, v213, v217, s[8:9]
	v_cndmask_b32_e64 v106, v214, v218, s[8:9]
	v_cndmask_b32_e64 v107, v215, v219, s[8:9]
	v_mov_b32_dpp v117, v104 row_ror:8 row_mask:0xf bank_mask:0xf
	v_mov_b32_dpp v118, v105 row_ror:8 row_mask:0xf bank_mask:0xf
	v_mov_b32_dpp v119, v106 row_ror:8 row_mask:0xf bank_mask:0xf
	v_mov_b32_dpp v120, v107 row_ror:8 row_mask:0xf bank_mask:0xf
	v_lshlrev_b32_e32 v104, 16, v4
	v_and_b32_e32 v105, 0xffff0000, v4
	v_lshlrev_b32_e32 v106, 16, v114
	v_and_b32_e32 v107, 0xffff0000, v114
	v_lshlrev_b32_e32 v108, 16, v115
	v_and_b32_e32 v109, 0xffff0000, v115
	v_lshlrev_b32_e32 v110, 16, v116
	v_and_b32_e32 v111, 0xffff0000, v116
	v_pk_mul_f32 v[102:103], v[102:103], v[106:107]
	v_pk_mul_f32 v[100:101], v[100:101], v[104:105]
	v_pk_mul_f32 v[98:99], v[98:99], v[110:111]
	v_pk_mul_f32 v[96:97], v[96:97], v[108:109]
	v_cvt_pk_bf16_f32 v4, v100, v101
	v_cvt_pk_bf16_f32 v100, v102, v103
	v_lshlrev_b32_e32 v104, 16, v119
	v_cvt_pk_bf16_f32 v101, v96, v97
	v_cvt_pk_bf16_f32 v102, v98, v99
	v_lshlrev_b32_e32 v96, 16, v117
	v_and_b32_e32 v97, 0xffff0000, v117
	v_lshlrev_b32_e32 v98, 16, v118
	v_and_b32_e32 v99, 0xffff0000, v118
	v_and_b32_e32 v105, 0xffff0000, v119
	v_lshlrev_b32_e32 v106, 16, v120
	v_and_b32_e32 v107, 0xffff0000, v120
	v_pk_mul_f32 v[94:95], v[94:95], v[98:99]
	v_pk_mul_f32 v[92:93], v[92:93], v[96:97]
	v_pk_mul_f32 v[90:91], v[90:91], v[106:107]
	v_pk_mul_f32 v[88:89], v[88:89], v[104:105]
	v_cvt_pk_bf16_f32 v92, v92, v93
	v_cvt_pk_bf16_f32 v93, v94, v95
	v_lshl_add_u64 v[96:97], s[40:41], 0, v[112:113]
	v_cvt_pk_bf16_f32 v94, v88, v89
	v_cvt_pk_bf16_f32 v95, v90, v91
	v_mov_b32_e32 v88, v5
	v_mov_b32_e32 v89, v5
	v_mov_b32_e32 v90, v5
	v_mov_b32_e32 v91, v5
	v_mov_b32_dpp v88, v92 row_ror:8 row_mask:0xf bank_mask:0xf
	v_mov_b32_dpp v89, v93 row_ror:8 row_mask:0xf bank_mask:0xf
	v_mov_b32_dpp v90, v94 row_ror:8 row_mask:0xf bank_mask:0xf
	v_mov_b32_dpp v91, v95 row_ror:8 row_mask:0xf bank_mask:0xf
	v_lshl_add_u64 v[98:99], v[96:97], 0, s[58:59]
	v_mov_b32_e32 v92, v4
	v_mov_b32_e32 v93, v100
	v_mov_b32_e32 v94, v101
	v_mov_b32_e32 v95, v102
	s_and_saveexec_b64 s[26:27], s[8:9]
	s_cbranch_execz .LBB0_790
	v_lshl_add_u64 v[104:105], v[96:97], 0, s[60:61]
	v_mov_b64_e32 v[98:99], v[96:97]
	v_mov_b32_e32 v92, v88
	v_mov_b32_e32 v93, v89
	v_mov_b32_e32 v94, v90
	v_mov_b32_e32 v95, v91
	v_mov_b32_e32 v88, v4
	v_mov_b32_e32 v89, v100
	v_mov_b32_e32 v90, v101
	v_mov_b32_e32 v91, v102
	v_mov_b64_e32 v[96:97], v[104:105]
.LBB0_790:
	s_or_b64 exec, exec, s[26:27]
	global_store_dwordx4 v[98:99], v[88:91], off
	global_store_dwordx4 v[96:97], v[92:95], off
	v_mov_b32_e32 v101, v5
	v_or_b32_e32 v88, 48, v136
	v_ashrrev_i32_e32 v89, 31, v88
	v_lshlrev_b64 v[88:89], 10, v[88:89]
	v_lshl_add_u64 v[88:89], v[88:89], 0, v[6:7]
	v_lshlrev_b64 v[96:97], 1, v[88:89]
	v_lshl_add_u64 v[88:89], s[46:47], 0, v[96:97]
	v_lshl_add_u64 v[90:91], v[88:89], 0, v[148:149]
	v_lshl_add_u64 v[92:93], v[88:89], 0, v[150:151]
	v_mov_b32_e32 v102, v5
	v_mov_b32_e32 v103, v5
	v_mov_b32_e32 v104, v5
	s_waitcnt vmcnt(14)
	v_cndmask_b32_e64 v4, v224, v220, s[8:9]
	v_cndmask_b32_e64 v98, v225, v221, s[8:9]
	v_cndmask_b32_e64 v99, v226, v222, s[8:9]
	v_cndmask_b32_e64 v100, v227, v223, s[8:9]
	v_cndmask_b32_e64 v88, v220, v224, s[8:9]
	v_cndmask_b32_e64 v89, v221, v225, s[8:9]
	v_cndmask_b32_e64 v90, v222, v226, s[8:9]
	v_cndmask_b32_e64 v91, v223, v227, s[8:9]
	v_mov_b32_dpp v101, v88 row_ror:8 row_mask:0xf bank_mask:0xf
	v_mov_b32_dpp v102, v89 row_ror:8 row_mask:0xf bank_mask:0xf
	v_mov_b32_dpp v103, v90 row_ror:8 row_mask:0xf bank_mask:0xf
	v_mov_b32_dpp v104, v91 row_ror:8 row_mask:0xf bank_mask:0xf
	v_lshlrev_b32_e32 v88, 16, v4
	v_and_b32_e32 v89, 0xffff0000, v4
	v_lshlrev_b32_e32 v90, 16, v98
	v_and_b32_e32 v91, 0xffff0000, v98
	v_lshlrev_b32_e32 v92, 16, v99
	v_and_b32_e32 v93, 0xffff0000, v99
	v_lshlrev_b32_e32 v94, 16, v100
	v_and_b32_e32 v95, 0xffff0000, v100
	v_pk_mul_f32 v[86:87], v[86:87], v[90:91]
	v_pk_mul_f32 v[84:85], v[84:85], v[88:89]
	v_pk_mul_f32 v[82:83], v[82:83], v[94:95]
	v_pk_mul_f32 v[80:81], v[80:81], v[92:93]
	v_cvt_pk_bf16_f32 v4, v84, v85
	v_cvt_pk_bf16_f32 v84, v86, v87
	v_lshlrev_b32_e32 v88, 16, v103
	v_cvt_pk_bf16_f32 v85, v80, v81
	v_cvt_pk_bf16_f32 v86, v82, v83
	v_lshlrev_b32_e32 v80, 16, v101
	v_and_b32_e32 v81, 0xffff0000, v101
	v_lshlrev_b32_e32 v82, 16, v102
	v_and_b32_e32 v83, 0xffff0000, v102
	v_and_b32_e32 v89, 0xffff0000, v103
	v_lshlrev_b32_e32 v90, 16, v104
	v_and_b32_e32 v91, 0xffff0000, v104
	v_pk_mul_f32 v[78:79], v[78:79], v[82:83]
	v_pk_mul_f32 v[76:77], v[76:77], v[80:81]
	v_pk_mul_f32 v[74:75], v[74:75], v[90:91]
	v_pk_mul_f32 v[72:73], v[72:73], v[88:89]
	v_cvt_pk_bf16_f32 v76, v76, v77
	v_cvt_pk_bf16_f32 v77, v78, v79
	v_lshl_add_u64 v[80:81], s[40:41], 0, v[96:97]
	v_cvt_pk_bf16_f32 v78, v72, v73
	v_cvt_pk_bf16_f32 v79, v74, v75
	v_mov_b32_e32 v72, v5
	v_mov_b32_e32 v73, v5
	v_mov_b32_e32 v74, v5
	v_mov_b32_e32 v75, v5
	v_mov_b32_dpp v72, v76 row_ror:8 row_mask:0xf bank_mask:0xf
	v_mov_b32_dpp v73, v77 row_ror:8 row_mask:0xf bank_mask:0xf
	v_mov_b32_dpp v74, v78 row_ror:8 row_mask:0xf bank_mask:0xf
	v_mov_b32_dpp v75, v79 row_ror:8 row_mask:0xf bank_mask:0xf
	v_lshl_add_u64 v[82:83], v[80:81], 0, s[58:59]
	v_mov_b32_e32 v76, v4
	v_mov_b32_e32 v77, v84
	v_mov_b32_e32 v78, v85
	v_mov_b32_e32 v79, v86
	s_and_saveexec_b64 s[26:27], s[8:9]
	s_cbranch_execz .LBB0_792
	v_lshl_add_u64 v[88:89], v[80:81], 0, s[60:61]
	v_mov_b64_e32 v[82:83], v[80:81]
	v_mov_b32_e32 v76, v72
	v_mov_b32_e32 v77, v73
	v_mov_b32_e32 v78, v74
	v_mov_b32_e32 v79, v75
	v_mov_b32_e32 v72, v4
	v_mov_b32_e32 v73, v84
	v_mov_b32_e32 v74, v85
	v_mov_b32_e32 v75, v86
	v_mov_b64_e32 v[80:81], v[88:89]
.LBB0_792:
	s_or_b64 exec, exec, s[26:27]
	global_store_dwordx4 v[82:83], v[72:75], off
	global_store_dwordx4 v[80:81], v[76:79], off
	v_mov_b32_e32 v87, v5
	v_lshlrev_b64 v[72:73], 10, v[136:137]
	v_lshl_add_u64 v[72:73], v[72:73], 0, v[6:7]
	v_lshl_add_u64 v[82:83], v[72:73], 1, v[162:163]
	v_lshl_add_u64 v[74:75], s[46:47], 0, v[82:83]
	v_lshl_add_u64 v[76:77], v[74:75], 0, v[148:149]
	v_lshl_add_u64 v[78:79], v[74:75], 0, v[150:151]
	v_mov_b32_e32 v88, v5
	v_mov_b32_e32 v89, v5
	v_mov_b32_e32 v90, v5
	s_waitcnt vmcnt(14)
	v_cndmask_b32_e64 v4, v232, v228, s[8:9]
	v_cndmask_b32_e64 v84, v233, v229, s[8:9]
	v_cndmask_b32_e64 v85, v234, v230, s[8:9]
	v_cndmask_b32_e64 v86, v235, v231, s[8:9]
	v_cndmask_b32_e64 v74, v228, v232, s[8:9]
	v_cndmask_b32_e64 v75, v229, v233, s[8:9]
	v_cndmask_b32_e64 v76, v230, v234, s[8:9]
	v_cndmask_b32_e64 v77, v231, v235, s[8:9]
	v_mov_b32_dpp v87, v74 row_ror:8 row_mask:0xf bank_mask:0xf
	v_mov_b32_dpp v88, v75 row_ror:8 row_mask:0xf bank_mask:0xf
	v_mov_b32_dpp v89, v76 row_ror:8 row_mask:0xf bank_mask:0xf
	v_mov_b32_dpp v90, v77 row_ror:8 row_mask:0xf bank_mask:0xf
	v_lshlrev_b32_e32 v74, 16, v4
	v_and_b32_e32 v75, 0xffff0000, v4
	v_lshlrev_b32_e32 v76, 16, v84
	v_and_b32_e32 v77, 0xffff0000, v84
	v_lshlrev_b32_e32 v78, 16, v85
	v_and_b32_e32 v79, 0xffff0000, v85
	v_lshlrev_b32_e32 v80, 16, v86
	v_and_b32_e32 v81, 0xffff0000, v86
	v_pk_mul_f32 v[70:71], v[70:71], v[76:77]
	v_pk_mul_f32 v[68:69], v[68:69], v[74:75]
	v_pk_mul_f32 v[66:67], v[66:67], v[80:81]
	v_pk_mul_f32 v[64:65], v[64:65], v[78:79]
	v_cvt_pk_bf16_f32 v4, v68, v69
	v_cvt_pk_bf16_f32 v68, v70, v71
	v_lshlrev_b32_e32 v74, 16, v89
	v_cvt_pk_bf16_f32 v69, v64, v65
	v_cvt_pk_bf16_f32 v70, v66, v67
	v_lshlrev_b32_e32 v64, 16, v87
	v_and_b32_e32 v65, 0xffff0000, v87
	v_lshlrev_b32_e32 v66, 16, v88
	v_and_b32_e32 v67, 0xffff0000, v88
	v_and_b32_e32 v75, 0xffff0000, v89
	v_lshlrev_b32_e32 v76, 16, v90
	v_and_b32_e32 v77, 0xffff0000, v90
	v_pk_mul_f32 v[62:63], v[62:63], v[66:67]
	v_pk_mul_f32 v[60:61], v[60:61], v[64:65]
	v_pk_mul_f32 v[58:59], v[58:59], v[76:77]
	v_pk_mul_f32 v[56:57], v[56:57], v[74:75]
	v_cvt_pk_bf16_f32 v60, v60, v61
	v_cvt_pk_bf16_f32 v61, v62, v63
	v_lshl_add_u64 v[64:65], s[40:41], 0, v[82:83]
	v_cvt_pk_bf16_f32 v62, v56, v57
	v_cvt_pk_bf16_f32 v63, v58, v59
	v_mov_b32_e32 v56, v5
	v_mov_b32_e32 v57, v5
	v_mov_b32_e32 v58, v5
	v_mov_b32_e32 v59, v5
	v_mov_b32_dpp v56, v60 row_ror:8 row_mask:0xf bank_mask:0xf
	v_mov_b32_dpp v57, v61 row_ror:8 row_mask:0xf bank_mask:0xf
	v_mov_b32_dpp v58, v62 row_ror:8 row_mask:0xf bank_mask:0xf
	v_mov_b32_dpp v59, v63 row_ror:8 row_mask:0xf bank_mask:0xf
	v_lshl_add_u64 v[66:67], v[64:65], 0, s[58:59]
	v_mov_b32_e32 v60, v4
	v_mov_b32_e32 v61, v68
	v_mov_b32_e32 v62, v69
	v_mov_b32_e32 v63, v70
	s_and_saveexec_b64 s[26:27], s[8:9]
	s_cbranch_execz .LBB0_794
	v_lshl_add_u64 v[74:75], v[64:65], 0, s[60:61]
	v_mov_b64_e32 v[66:67], v[64:65]
	v_mov_b32_e32 v60, v56
	v_mov_b32_e32 v61, v57
	v_mov_b32_e32 v62, v58
	v_mov_b32_e32 v63, v59
	v_mov_b32_e32 v56, v4
	v_mov_b32_e32 v57, v68
	v_mov_b32_e32 v58, v69
	v_mov_b32_e32 v59, v70
	v_mov_b64_e32 v[64:65], v[74:75]
.LBB0_794:
	s_or_b64 exec, exec, s[26:27]
	global_store_dwordx4 v[66:67], v[56:59], off
	global_store_dwordx4 v[64:65], v[60:63], off
	v_lshl_add_u64 v[64:65], v[72:73], 1, v[164:165]
	v_lshl_add_u64 v[56:57], s[46:47], 0, v[64:65]
	v_lshl_add_u64 v[58:59], v[56:57], 0, v[148:149]
	v_lshl_add_u64 v[60:61], v[56:57], 0, v[150:151]
	v_mov_b32_e32 v69, v5
	v_mov_b32_e32 v70, v5
	v_mov_b32_e32 v71, v5
	v_mov_b32_e32 v72, v5
	s_waitcnt vmcnt(14)
	v_cndmask_b32_e64 v4, v240, v236, s[8:9]
	v_cndmask_b32_e64 v66, v241, v237, s[8:9]
	v_cndmask_b32_e64 v67, v242, v238, s[8:9]
	v_cndmask_b32_e64 v68, v243, v239, s[8:9]
	v_cndmask_b32_e64 v56, v236, v240, s[8:9]
	v_cndmask_b32_e64 v57, v237, v241, s[8:9]
	v_cndmask_b32_e64 v58, v238, v242, s[8:9]
	v_cndmask_b32_e64 v59, v239, v243, s[8:9]
	v_mov_b32_dpp v69, v56 row_ror:8 row_mask:0xf bank_mask:0xf
	v_mov_b32_dpp v70, v57 row_ror:8 row_mask:0xf bank_mask:0xf
	v_mov_b32_dpp v71, v58 row_ror:8 row_mask:0xf bank_mask:0xf
	v_mov_b32_dpp v72, v59 row_ror:8 row_mask:0xf bank_mask:0xf
	v_lshlrev_b32_e32 v56, 16, v4
	v_and_b32_e32 v57, 0xffff0000, v4
	v_lshlrev_b32_e32 v58, 16, v66
	v_and_b32_e32 v59, 0xffff0000, v66
	v_lshlrev_b32_e32 v60, 16, v67
	v_and_b32_e32 v61, 0xffff0000, v67
	v_lshlrev_b32_e32 v62, 16, v68
	v_and_b32_e32 v63, 0xffff0000, v68
	v_pk_mul_f32 v[54:55], v[54:55], v[58:59]
	v_pk_mul_f32 v[52:53], v[52:53], v[56:57]
	v_pk_mul_f32 v[50:51], v[50:51], v[62:63]
	v_pk_mul_f32 v[48:49], v[48:49], v[60:61]
	v_cvt_pk_bf16_f32 v4, v52, v53
	v_cvt_pk_bf16_f32 v52, v54, v55
	v_lshlrev_b32_e32 v56, 16, v71
	v_cvt_pk_bf16_f32 v53, v48, v49
	v_cvt_pk_bf16_f32 v54, v50, v51
	v_lshlrev_b32_e32 v48, 16, v69
	v_and_b32_e32 v49, 0xffff0000, v69
	v_lshlrev_b32_e32 v50, 16, v70
	v_and_b32_e32 v51, 0xffff0000, v70
	v_and_b32_e32 v57, 0xffff0000, v71
	v_lshlrev_b32_e32 v58, 16, v72
	v_and_b32_e32 v59, 0xffff0000, v72
	v_pk_mul_f32 v[46:47], v[46:47], v[50:51]
	v_pk_mul_f32 v[44:45], v[44:45], v[48:49]
	v_pk_mul_f32 v[42:43], v[42:43], v[58:59]
	v_pk_mul_f32 v[40:41], v[40:41], v[56:57]
	v_cvt_pk_bf16_f32 v44, v44, v45
	v_cvt_pk_bf16_f32 v45, v46, v47
	v_lshl_add_u64 v[48:49], s[40:41], 0, v[64:65]
	v_cvt_pk_bf16_f32 v46, v40, v41
	v_cvt_pk_bf16_f32 v47, v42, v43
	v_mov_b32_e32 v40, v5
	v_mov_b32_e32 v41, v5
	v_mov_b32_e32 v42, v5
	v_mov_b32_e32 v43, v5
	v_mov_b32_dpp v40, v44 row_ror:8 row_mask:0xf bank_mask:0xf
	v_mov_b32_dpp v41, v45 row_ror:8 row_mask:0xf bank_mask:0xf
	v_mov_b32_dpp v42, v46 row_ror:8 row_mask:0xf bank_mask:0xf
	v_mov_b32_dpp v43, v47 row_ror:8 row_mask:0xf bank_mask:0xf
	v_lshl_add_u64 v[50:51], v[48:49], 0, s[58:59]
	v_mov_b32_e32 v44, v4
	v_mov_b32_e32 v45, v52
	v_mov_b32_e32 v46, v53
	v_mov_b32_e32 v47, v54
	s_and_saveexec_b64 s[26:27], s[8:9]
	s_cbranch_execz .LBB0_796
	v_lshl_add_u64 v[56:57], v[48:49], 0, s[60:61]
	v_mov_b64_e32 v[50:51], v[48:49]
	v_mov_b32_e32 v44, v40
	v_mov_b32_e32 v45, v41
	v_mov_b32_e32 v46, v42
	v_mov_b32_e32 v47, v43
	v_mov_b32_e32 v40, v4
	v_mov_b32_e32 v41, v52
	v_mov_b32_e32 v42, v53
	v_mov_b32_e32 v43, v54
	v_mov_b64_e32 v[48:49], v[56:57]
.LBB0_796:
	s_or_b64 exec, exec, s[26:27]
	global_store_dwordx4 v[50:51], v[40:43], off
	global_store_dwordx4 v[48:49], v[44:47], off
	v_mov_b32_e32 v53, v5
	v_lshlrev_b64 v[40:41], 10, v[136:137]
	v_lshl_add_u64 v[6:7], v[40:41], 0, v[6:7]
	v_lshl_add_u64 v[48:49], v[6:7], 1, v[166:167]
	v_lshl_add_u64 v[40:41], s[46:47], 0, v[48:49]
	v_lshl_add_u64 v[42:43], v[40:41], 0, v[148:149]
	v_lshl_add_u64 v[44:45], v[40:41], 0, v[150:151]
	v_mov_b32_e32 v54, v5
	v_mov_b32_e32 v55, v5
	v_mov_b32_e32 v56, v5
	s_waitcnt vmcnt(14)
	v_cndmask_b32_e64 v4, v200, v196, s[8:9]
	v_cndmask_b32_e64 v50, v201, v197, s[8:9]
	v_cndmask_b32_e64 v51, v202, v198, s[8:9]
	v_cndmask_b32_e64 v52, v203, v199, s[8:9]
	v_cndmask_b32_e64 v40, v196, v200, s[8:9]
	v_cndmask_b32_e64 v41, v197, v201, s[8:9]
	v_cndmask_b32_e64 v42, v198, v202, s[8:9]
	v_cndmask_b32_e64 v43, v199, v203, s[8:9]
	v_mov_b32_dpp v53, v40 row_ror:8 row_mask:0xf bank_mask:0xf
	v_mov_b32_dpp v54, v41 row_ror:8 row_mask:0xf bank_mask:0xf
	v_mov_b32_dpp v55, v42 row_ror:8 row_mask:0xf bank_mask:0xf
	v_mov_b32_dpp v56, v43 row_ror:8 row_mask:0xf bank_mask:0xf
	v_lshlrev_b32_e32 v40, 16, v4
	v_and_b32_e32 v41, 0xffff0000, v4
	v_lshlrev_b32_e32 v42, 16, v50
	v_and_b32_e32 v43, 0xffff0000, v50
	v_lshlrev_b32_e32 v44, 16, v51
	v_and_b32_e32 v45, 0xffff0000, v51
	v_lshlrev_b32_e32 v46, 16, v52
	v_and_b32_e32 v47, 0xffff0000, v52
	v_pk_mul_f32 v[38:39], v[38:39], v[42:43]
	v_pk_mul_f32 v[36:37], v[36:37], v[40:41]
	v_pk_mul_f32 v[34:35], v[34:35], v[46:47]
	v_pk_mul_f32 v[32:33], v[32:33], v[44:45]
	v_cvt_pk_bf16_f32 v4, v36, v37
	v_cvt_pk_bf16_f32 v36, v38, v39
	v_lshlrev_b32_e32 v40, 16, v55
	v_cvt_pk_bf16_f32 v37, v32, v33
	v_cvt_pk_bf16_f32 v38, v34, v35
	v_lshlrev_b32_e32 v32, 16, v53
	v_and_b32_e32 v33, 0xffff0000, v53
	v_lshlrev_b32_e32 v34, 16, v54
	v_and_b32_e32 v35, 0xffff0000, v54
	v_and_b32_e32 v41, 0xffff0000, v55
	v_lshlrev_b32_e32 v42, 16, v56
	v_and_b32_e32 v43, 0xffff0000, v56
	v_pk_mul_f32 v[30:31], v[30:31], v[34:35]
	v_pk_mul_f32 v[28:29], v[28:29], v[32:33]
	v_pk_mul_f32 v[26:27], v[26:27], v[42:43]
	v_pk_mul_f32 v[24:25], v[24:25], v[40:41]
	v_cvt_pk_bf16_f32 v28, v28, v29
	v_cvt_pk_bf16_f32 v29, v30, v31
	v_lshl_add_u64 v[32:33], s[40:41], 0, v[48:49]
	v_cvt_pk_bf16_f32 v30, v24, v25
	v_cvt_pk_bf16_f32 v31, v26, v27
	v_mov_b32_e32 v24, v5
	v_mov_b32_e32 v25, v5
	v_mov_b32_e32 v26, v5
	v_mov_b32_e32 v27, v5
	v_mov_b32_dpp v24, v28 row_ror:8 row_mask:0xf bank_mask:0xf
	v_mov_b32_dpp v25, v29 row_ror:8 row_mask:0xf bank_mask:0xf
	v_mov_b32_dpp v26, v30 row_ror:8 row_mask:0xf bank_mask:0xf
	v_mov_b32_dpp v27, v31 row_ror:8 row_mask:0xf bank_mask:0xf
	v_lshl_add_u64 v[34:35], v[32:33], 0, s[58:59]
	v_mov_b32_e32 v28, v4
	v_mov_b32_e32 v29, v36
	v_mov_b32_e32 v30, v37
	v_mov_b32_e32 v31, v38
	s_and_saveexec_b64 s[26:27], s[8:9]
	s_cbranch_execz .LBB0_798
	v_lshl_add_u64 v[40:41], v[32:33], 0, s[60:61]
	v_mov_b64_e32 v[34:35], v[32:33]
	v_mov_b32_e32 v28, v24
	v_mov_b32_e32 v29, v25
	v_mov_b32_e32 v30, v26
	v_mov_b32_e32 v31, v27
	v_mov_b32_e32 v24, v4
	v_mov_b32_e32 v25, v36
	v_mov_b32_e32 v26, v37
	v_mov_b32_e32 v27, v38
	v_mov_b64_e32 v[32:33], v[40:41]
.LBB0_798:
	s_or_b64 exec, exec, s[26:27]
	v_lshl_add_u64 v[6:7], v[6:7], 1, v[168:169]
	global_store_dwordx4 v[34:35], v[24:27], off
	global_store_dwordx4 v[32:33], v[28:31], off
	v_mov_b32_e32 v35, v5
	v_lshl_add_u64 v[24:25], s[46:47], 0, v[6:7]
	v_lshl_add_u64 v[26:27], v[24:25], 0, v[148:149]
	v_lshl_add_u64 v[28:29], v[24:25], 0, v[150:151]
	v_mov_b32_e32 v36, v5
	v_mov_b32_e32 v37, v5
	v_mov_b32_e32 v38, v5
	s_waitcnt vmcnt(12)
	v_cndmask_b32_e64 v4, v208, v204, s[8:9]
	v_cndmask_b32_e64 v32, v209, v205, s[8:9]
	v_cndmask_b32_e64 v33, v210, v206, s[8:9]
	v_cndmask_b32_e64 v34, v211, v207, s[8:9]
	v_cndmask_b32_e64 v24, v204, v208, s[8:9]
	v_cndmask_b32_e64 v25, v205, v209, s[8:9]
	v_cndmask_b32_e64 v26, v206, v210, s[8:9]
	v_cndmask_b32_e64 v27, v207, v211, s[8:9]
	v_mov_b32_dpp v35, v24 row_ror:8 row_mask:0xf bank_mask:0xf
	v_mov_b32_dpp v36, v25 row_ror:8 row_mask:0xf bank_mask:0xf
	v_lshlrev_b32_e32 v24, 16, v4
	v_and_b32_e32 v25, 0xffff0000, v4
	v_lshlrev_b32_e32 v28, 16, v33
	v_and_b32_e32 v29, 0xffff0000, v33
	v_lshlrev_b32_e32 v30, 16, v34
	v_and_b32_e32 v31, 0xffff0000, v34
	v_mov_b32_dpp v37, v26 row_ror:8 row_mask:0xf bank_mask:0xf
	v_mov_b32_dpp v38, v27 row_ror:8 row_mask:0xf bank_mask:0xf
	v_lshlrev_b32_e32 v26, 16, v32
	v_and_b32_e32 v27, 0xffff0000, v32
	v_pk_mul_f32 v[20:21], v[20:21], v[24:25]
	v_pk_mul_f32 v[24:25], v[18:19], v[30:31]
	v_pk_mul_f32 v[16:17], v[16:17], v[28:29]
	v_pk_mul_f32 v[22:23], v[22:23], v[26:27]
	v_cvt_pk_bf16_f32 v4, v20, v21
	v_lshlrev_b32_e32 v26, 16, v38
	v_cvt_pk_bf16_f32 v18, v22, v23
	v_cvt_pk_bf16_f32 v19, v16, v17
	v_cvt_pk_bf16_f32 v20, v24, v25
	v_lshlrev_b32_e32 v16, 16, v35
	v_and_b32_e32 v17, 0xffff0000, v35
	v_lshlrev_b32_e32 v24, 16, v37
	v_and_b32_e32 v25, 0xffff0000, v37
	v_lshlrev_b32_e32 v22, 16, v36
	v_and_b32_e32 v23, 0xffff0000, v36
	v_and_b32_e32 v27, 0xffff0000, v38
	v_pk_mul_f32 v[12:13], v[12:13], v[16:17]
	v_pk_mul_f32 v[8:9], v[8:9], v[24:25]
	v_pk_mul_f32 v[14:15], v[14:15], v[22:23]
	v_pk_mul_f32 v[10:11], v[10:11], v[26:27]
	v_cvt_pk_bf16_f32 v12, v12, v13
	v_cvt_pk_bf16_f32 v13, v14, v15
	v_cvt_pk_bf16_f32 v9, v8, v9
	v_mov_b32_e32 v8, v5
	v_cvt_pk_bf16_f32 v10, v10, v11
	v_lshl_add_u64 v[14:15], s[40:41], 0, v[6:7]
	v_mov_b32_e32 v6, v5
	v_mov_b32_e32 v7, v5
	v_mov_b32_dpp v8, v9 row_ror:8 row_mask:0xf bank_mask:0xf
	v_mov_b32_e32 v9, v5
	v_mov_b32_dpp v6, v12 row_ror:8 row_mask:0xf bank_mask:0xf
	v_mov_b32_dpp v7, v13 row_ror:8 row_mask:0xf bank_mask:0xf
	v_mov_b32_dpp v9, v10 row_ror:8 row_mask:0xf bank_mask:0xf
	v_lshl_add_u64 v[16:17], v[14:15], 0, s[58:59]
	v_mov_b32_e32 v10, v4
	v_mov_b32_e32 v11, v18
	v_mov_b32_e32 v12, v19
	v_mov_b32_e32 v13, v20
	s_and_saveexec_b64 s[26:27], s[8:9]
	s_cbranch_execz .LBB0_800
	v_lshl_add_u64 v[22:23], v[14:15], 0, s[60:61]
	v_mov_b64_e32 v[16:17], v[14:15]
	v_mov_b32_e32 v10, v6
	v_mov_b32_e32 v11, v7
	v_mov_b32_e32 v12, v8
	v_mov_b32_e32 v13, v9
	v_mov_b32_e32 v6, v4
	v_mov_b32_e32 v7, v18
	v_mov_b32_e32 v8, v19
	v_mov_b32_e32 v9, v20
	v_mov_b64_e32 v[14:15], v[22:23]
